# MLA fast loop: K/kr tile-load addresses from 3 per-item base pointers + scalar row offsets (10 VALU incl. five 64-bit ops -> 3 v_lshl_add_u64 per tile)
# speedup vs baseline: 1.0065x; 1.0029x over previous
; #define LAS __attribute__((address_space(3)))
; template <int DQ>
; DI void attn_item(const Frame& F, const AttnItem& it, const LAS float* rpb_lds) {
;     ...
;     int tid = threadIdx.x; asm volatile("" : "+v"(tid));
;     const int lane = tid & 63, w = __builtin_amdgcn_readfirstlane(tid >> 6), qq = lane & 31, hh = lane >> 5;
;     const bool grpB = w >= 4;
;     const int ntile = it.ntl + it.nctx;
;     u32x4 rk[2], rr, rv[2];
;     auto gload = [&](int ti) {
;         int rowb, vcol;
;         if (ti < it.ntl) { const int kt = it.t0 + ti; rowb = it.lat_row0 + kt * 64; vcol = kt * 64; } else { const int j = ti - it.ntl; rowb = it.ctx_row0 + j * 64; vcol = SEQ + j * 64; }
; #pragma unroll
;         for (int i = 0; i < 2; ++i) { const int id = tid + i * NT; rk[i] = *(const u32x4*)(it.kn + (size_t)(rowb + (id >> 4)) * it.ldk + (id & 15) * 8);
;             rv[i] = *(const u32x4*)(it.vt + (size_t)(id >> 3) * KEYS + vcol + (id & 7) * 8); }
;         if (DQ == 192) rr = *(const u32x4*)(it.kr + (size_t)(rowb + (tid >> 3)) * UC + (tid & 7) * 8);
;     };
;     auto lstore = [&](int ti) {
;         LAS unsigned char* kb = base + (ti & 1) * KBYTES; LAS unsigned char* vb = base + 2 * KBYTES + (ti % 3) * VBYTES;
; #pragma unroll
;         for (int i = 0; i < 2; ++i) { const int id = tid + i * NT; *(LAS u32x4*)(kb + ((id >> 4) * KP + (id & 15) * 8) * 2) = rk[i];
;             *(LAS u32x4*)(vb + ((id >> 3) * VP + (id & 7) * 8) * 2) = rv[i]; }
;         if (DQ == 192) *(LAS u32x4*)(kb + ((tid >> 3) * KP + 128 + (tid & 7) * 8) * 2) = rr;
;     };
;     bf16x8 qf[KS];
;     { const bf16_t* qp = it.q + (size_t)(32 * w + qq) * it.ldq + 8 * hh;
; #pragma unroll
;         for (int ks = 0; ks < KS; ++ks) qf[ks] = *(const bf16x8*)(qp + 16 * ks); }
.LBB0_1346:
	s_and_b32 s7, s40, 7
	s_ashr_i32 s1, s0, 31
	s_mul_i32 s4, s0, 0xc00
	v_readlane_b32 s5, v255, 26
	s_mul_hi_i32 s2, s0, 0xc00
	s_add_u32 s4, s5, s4
	v_readlane_b32 s5, v255, 27
	s_addc_u32 s2, s5, s2
	s_mul_i32 s5, s7, 0x180
	s_add_u32 s10, s4, s5
	s_addc_u32 s11, s2, 0
	s_lshl_b32 s2, s7, 7
	s_lshl_b32 s4, s7, 8
	v_readlane_b32 s5, v255, 28
	s_add_u32 s4, s5, s4
	v_readlane_b32 s5, v255, 29
	s_addc_u32 s5, s5, 0
	s_lshl_b32 s8, s8, 3
	s_or_b32 s7, s8, s7
	s_mul_hi_i32 s8, s7, 0x110000
	s_mul_i32 s7, s7, 0x110000
	v_readlane_b32 s9, v255, 30
	s_add_u32 s12, s9, s7
	v_readlane_b32 s7, v255, 31
	v_mov_b32_e32 v39, v192
	s_addc_u32 s13, s7, s8
	v_mov_b64_e32 v[2:3], s[10:11]
	v_readfirstlane_b32 s7, v39
	s_ashr_i32 s7, s7, 6
	v_and_b32_e32 v50, 31, v39
	v_lshl_or_b32 v184, s7, 5, v50
	v_mad_i64_i32 v[2:3], s[8:9], v184, s95, v[2:3]
	s_cmp_gt_i32 s7, 3
	s_cselect_b64 s[8:9], -1, 0
	s_cmp_lt_i32 s7, 4
	s_cselect_b64 s[10:11], -1, 0
	s_lshl_b32 s20, s3, 6
	v_readlane_b32 s24, v255, 0
	s_sub_i32 s7, s15, s20
	v_readlane_b32 s25, v255, 1
	s_and_b64 s[18:19], s[24:25], exec
	s_cselect_b32 s17, s14, s7
	v_ashrrev_i32_e32 v206, 4, v39
	v_add_u32_e32 v14, s17, v206
	v_ashrrev_i32_e32 v15, 31, v14
	v_lshlrev_b32_e32 v18, 3, v39
	v_ashrrev_i32_e32 v207, 3, v39
	v_mov_b64_e32 v[26:27], s[12:13]
	v_bfe_u32 v202, v39, 5, 1
	v_lshlrev_b64 v[14:15], 11, v[14:15]
	v_and_b32_e32 v51, 0x78, v18
	v_mad_i64_i32 v[36:37], s[12:13], v207, s85, v[26:27]
	s_lshl_b32 s56, s6, 1
	v_and_b32_e32 v38, 56, v18
	s_waitcnt lgkmcnt(0)
	v_lshlrev_b32_e32 v0, 4, v202
	v_lshl_add_u64 v[14:15], s[4:5], 0, v[14:15]
	v_lshlrev_b32_e32 v34, 1, v51
	v_mov_b32_e32 v35, v1
	v_lshl_add_u64 v[16:17], v[36:37], 0, s[56:57]
	v_lshlrev_b32_e32 v40, 1, v38
	v_mov_b32_e32 v41, v1
	v_lshl_add_u64 v[2:3], v[2:3], 0, v[0:1]
	v_lshl_add_u64 v[14:15], v[14:15], 0, v[34:35]
	v_lshl_add_u64 v[18:19], v[16:17], 0, v[40:41]
	v_add_u32_e32 v28, 0x200, v39
	global_load_dwordx4 v[144:147], v[2:3], off
	global_load_dwordx4 v[140:143], v[2:3], off offset:32
	global_load_dwordx4 v[136:139], v[2:3], off offset:64
	global_load_dwordx4 v[132:135], v[2:3], off offset:96
	global_load_dwordx4 v[128:131], v[2:3], off offset:128
	global_load_dwordx4 v[124:127], v[2:3], off offset:160
	global_load_dwordx4 v[120:123], v[2:3], off offset:192
	global_load_dwordx4 v[116:119], v[2:3], off offset:224
	global_load_dwordx4 v[112:115], v[2:3], off offset:256
	global_load_dwordx4 v[10:13], v[2:3], off offset:288
	global_load_dwordx4 v[6:9], v[2:3], off offset:320
	s_nop 0
	global_load_dwordx4 v[2:5], v[2:3], off offset:352
	s_barrier
; #define LAS __attribute__((address_space(3)))
; template <int DQ>
; DI void attn_item(const Frame& F, const AttnItem& it, const LAS float* rpb_lds) {
;     ...
;     auto gload = [&](int ti) {
;         int rowb, vcol;
;         if (ti < it.ntl) { const int kt = it.t0 + ti; rowb = it.lat_row0 + kt * 64; vcol = kt * 64; } else { const int j = ti - it.ntl; rowb = it.ctx_row0 + j * 64; vcol = SEQ + j * 64; }
; #pragma unroll
;         for (int i = 0; i < 2; ++i) { const int id = tid + i * NT; rk[i] = *(const u32x4*)(it.kn + (size_t)(rowb + (id >> 4)) * it.ldk + (id & 15) * 8);
;             rv[i] = *(const u32x4*)(it.vt + (size_t)(id >> 3) * KEYS + vcol + (id & 7) * 8); }
;         if (DQ == 192) rr = *(const u32x4*)(it.kr + (size_t)(rowb + (tid >> 3)) * UC + (tid & 7) * 8);
;     };
;     auto lstore = [&](int ti) {
;         LAS unsigned char* kb = base + (ti & 1) * KBYTES; LAS unsigned char* vb = base + 2 * KBYTES + (ti % 3) * VBYTES;
; #pragma unroll
;         for (int i = 0; i < 2; ++i) { const int id = tid + i * NT; *(LAS u32x4*)(kb + ((id >> 4) * KP + (id & 15) * 8) * 2) = rk[i];
;             *(LAS u32x4*)(vb + ((id >> 3) * VP + (id & 7) * 8) * 2) = rv[i]; }
;         if (DQ == 192) *(LAS u32x4*)(kb + ((tid >> 3) * KP + 128 + (tid & 7) * 8) * 2) = rr;
;     };
;     bf16x8 qf[KS];
;     { const bf16_t* qp = it.q + (size_t)(32 * w + qq) * it.ldq + 8 * hh;
; #pragma unroll
;         for (int ks = 0; ks < KS; ++ks) qf[ks] = *(const bf16x8*)(qp + 16 * ks); }
;     f32x16 o[4];
; #pragma unroll
;     for (int db = 0; db < 4; ++db)
; #pragma unroll
;         for (int i = 0; i < 16; ++i) o[db][i] = 0.f;
;     f32x16 s[2];
;     float mrun = -INFINITY, lrun = 0.f;
;     ...
;     __syncthreads();
;     gload(0); lstore(0);
;     if (ntile > 1) gload(1);
;     __syncthreads();
	global_load_dwordx4 v[14:17], v[14:15], off
	s_nop 0
	global_load_dwordx4 v[18:21], v[18:19], off
	v_ashrrev_i32_e32 v208, 4, v28
	v_add_u32_e32 v22, s17, v208
	v_ashrrev_i32_e32 v23, 31, v22
	v_ashrrev_i32_e32 v52, 3, v28
	v_readlane_b32 s22, v255, 38
	v_lshlrev_b64 v[22:23], 11, v[22:23]
	v_mad_i64_i32 v[42:43], s[6:7], v52, s85, v[26:27]
	v_readlane_b32 s23, v255, 39
	v_lshl_add_u64 v[22:23], s[4:5], 0, v[22:23]
	v_lshl_add_u64 v[26:27], v[42:43], 0, s[56:57]
	v_add_u32_e32 v30, s17, v207
	v_mov_b64_e32 v[44:45], s[22:23]
	s_sub_i32 s12, 0x1040, s20
	v_lshl_add_u64 v[22:23], v[22:23], 0, v[34:35]
	v_lshl_add_u64 v[26:27], v[26:27], 0, v[40:41]
	v_mad_i64_i32 v[30:31], s[6:7], v30, s63, v[44:45]
	s_and_b64 s[6:7], s[24:25], exec
	global_load_dwordx4 v[22:25], v[22:23], off
	s_cselect_b32 s6, 64, s12
	global_load_dwordx4 v[26:29], v[26:27], off
	s_or_b32 s7, s17, 64
	v_add_u32_e32 v46, s7, v206
	v_ashrrev_i32_e32 v47, 31, v46
	v_lshlrev_b64 v[46:47], 11, v[46:47]
	v_add_u32_e32 v48, s7, v208
	v_lshl_add_u64 v[46:47], s[4:5], 0, v[46:47]
	v_ashrrev_i32_e32 v49, 31, v48
	v_lshl_add_u64 v[30:31], v[30:31], 0, v[40:41]
	v_lshl_add_u64 v[46:47], v[46:47], 0, v[34:35]
	s_lshl_b32 s56, s6, 1
	v_lshlrev_b64 v[48:49], 11, v[48:49]
	global_load_dwordx4 v[30:33], v[30:31], off
	v_lshl_add_u64 v[48:49], s[4:5], 0, v[48:49]
	global_load_dwordx4 v[164:167], v[46:47], off
	v_lshl_add_u64 v[46:47], v[36:37], 0, s[56:57]
	v_lshl_add_u64 v[46:47], v[46:47], 0, v[40:41]
	v_lshl_add_u64 v[48:49], v[48:49], 0, v[34:35]
	global_load_dwordx4 v[160:163], v[46:47], off
	global_load_dwordx4 v[156:159], v[48:49], off
	v_lshl_add_u64 v[46:47], v[42:43], 0, s[56:57]
	v_add_u32_e32 v48, s7, v207
	v_lshl_add_u64 v[46:47], v[46:47], 0, v[40:41]
	v_mad_i64_i32 v[44:45], s[6:7], v48, s63, v[44:45]
	v_lshl_add_u64 v[44:45], v[44:45], 0, v[40:41]
	global_load_dwordx4 v[152:155], v[46:47], off
	global_load_dwordx4 v[148:151], v[44:45], off
	s_movk_i32 s7, 0xc8
	v_mul_lo_u32 v45, v206, s7
	v_add_lshl_u32 v209, v45, v51, 1
	v_add_u32_e32 v186, 0, v209
	s_movk_i32 s6, 0x48
	v_and_b32_e32 v44, 63, v39
	v_add_u32_e32 v203, 0, v0
	v_mul_u32_u24_e32 v204, 0x90, v50
	s_waitcnt vmcnt(23)
	v_lshl_add_u64 v[168:169], v[36:37], 0, v[40:41]
	v_lshl_add_u64 v[170:171], v[42:43], 0, v[40:41]
	s_waitcnt vmcnt(22)
	v_lshl_add_u64 v[172:173], s[22:23], 0, v[40:41]
	v_ashrrev_i32_e32 v185, 31, v184
	s_mov_b32 s17, 1
	s_mov_b32 s18, 2
	s_sub_i32 s19, 0x1080, s20
	s_sub_i32 s20, 0, s3
	v_mov_b32_e32 v174, 0xff800000
	v_mov_b32_e32 v216, 0
	s_waitcnt vmcnt(9)
	ds_write_b128 v186, v[14:17]
	v_mul_lo_u32 v14, v207, s6
	v_add_lshl_u32 v187, v14, v38, 1
	v_add_u32_e32 v14, 0, v187
	s_waitcnt vmcnt(8)
	ds_write_b128 v14, v[18:21] offset:51200
	v_mul_lo_u32 v14, v208, s7
	v_add_lshl_u32 v210, v14, v51, 1
	v_mul_lo_u32 v14, v52, s6
	v_add_lshl_u32 v189, v14, v38, 1
	v_add_u32_e32 v188, 0, v210
	v_add_u32_e32 v14, 0, v189
	v_and_b32_e32 v16, 19, v39
	v_lshlrev_b32_e32 v17, 4, v39
	v_and_b32_e32 v17, 0x70, v17
	v_mov_b32_e32 v18, v1
	v_mov_b32_e32 v19, v1
	v_mov_b32_e32 v20, v1
	v_mov_b32_e32 v21, v1
	s_waitcnt vmcnt(7)
	ds_write_b128 v188, v[22:25]
	v_mov_b32_e32 v22, v1
	s_waitcnt vmcnt(6)
	ds_write_b128 v14, v[26:29] offset:51200
	v_mad_u64_u32 v[14:15], s[6:7], v207, s7, v[38:39]
	v_lshl_add_u32 v211, v14, 1, v201
	v_lshrrev_b32_e32 v14, 1, v39
	v_lshlrev_b32_e32 v15, 1, v39
	v_and_b32_e32 v14, 4, v14
	v_and_b32_e32 v15, 8, v15
	v_or3_b32 v14, v16, v14, v15
	s_movk_i32 s6, 0x190
	v_mul_u32_u24_e32 v191, 0x190, v14
	v_mad_u32_u24 v212, v14, s6, v203
	v_lshlrev_b32_e32 v14, 2, v44
	v_xor_b32_e32 v175, 0x80, v14
	v_lshl_add_u64 v[14:15], s[4:5], 0, v[34:35]
	s_movk_i32 s4, 0x90
	v_add_u32_e32 v190, 0, v211
	v_mul_lo_u32 v16, v52, s4
	s_mov_b32 s5, 0x11000
	s_waitcnt vmcnt(5)
	ds_write_b128 v190, v[30:33]
	v_add3_u32 v213, v16, v17, s5
	v_mul_lo_u32 v16, v207, s4
	v_mov_b32_e32 v30, v1
	v_mov_b32_e32 v31, v1
	v_add3_u32 v214, v16, v17, s5
	s_mov_b32 s4, 0xc800
	v_mov_b32_e32 v16, v1
	v_mov_b32_e32 v17, v1
	v_mov_b32_e32 v23, v1
	v_mov_b32_e32 v24, v1
	v_mov_b32_e32 v25, v1
	v_mov_b32_e32 v26, v1
	v_mov_b32_e32 v27, v1
	v_mov_b32_e32 v28, v1
	v_mov_b32_e32 v29, v1
	v_mov_b64_e32 v[46:47], v[30:31]
	v_mov_b64_e32 v[62:63], v[30:31]
	v_mov_b64_e32 v[78:79], v[30:31]
	v_add3_u32 v215, v204, v0, s4
	v_mov_b64_e32 v[44:45], v[28:29]
	v_mov_b64_e32 v[42:43], v[26:27]
	v_mov_b64_e32 v[40:41], v[24:25]
	v_mov_b64_e32 v[38:39], v[22:23]
	v_mov_b64_e32 v[36:37], v[20:21]
	v_mov_b64_e32 v[34:35], v[18:19]
	v_mov_b64_e32 v[32:33], v[16:17]
	v_mov_b64_e32 v[60:61], v[28:29]
	v_mov_b64_e32 v[58:59], v[26:27]
	v_mov_b64_e32 v[56:57], v[24:25]
	v_mov_b64_e32 v[54:55], v[22:23]
	v_mov_b64_e32 v[52:53], v[20:21]
	v_mov_b64_e32 v[50:51], v[18:19]
	v_mov_b64_e32 v[48:49], v[16:17]
	v_mov_b64_e32 v[76:77], v[28:29]
	v_mov_b64_e32 v[74:75], v[26:27]
	v_mov_b64_e32 v[72:73], v[24:25]
	v_mov_b64_e32 v[70:71], v[22:23]
	v_mov_b64_e32 v[68:69], v[20:21]
	v_mov_b64_e32 v[66:67], v[18:19]
	v_mov_b64_e32 v[64:65], v[16:17]
	s_waitcnt lgkmcnt(0)
	s_barrier
	s_mov_b32 s32, 0xc2000000
	v_lshlrev_b32_e32 v194, 11, v206
	v_mov_b32_e32 v195, 0
	v_lshl_add_u64 v[194:195], v[14:15], 0, v[194:195]
	v_lshlrev_b32_e32 v196, 11, v208
	v_mov_b32_e32 v197, 0
	v_lshl_add_u64 v[196:197], v[14:15], 0, v[196:197]
	v_mad_i64_i32 v[198:199], s[98:99], v207, s63, v[172:173]

; template <int DQ>
; DI void attn_item(const Frame& F, const AttnItem& it, const LAS float* rpb_lds) {
;     ...
;     auto gload = [&](int ti) {
;         int rowb, vcol;
;         if (ti < it.ntl) { const int kt = it.t0 + ti; rowb = it.lat_row0 + kt * 64; vcol = kt * 64; } else { const int j = ti - it.ntl; rowb = it.ctx_row0 + j * 64; vcol = SEQ + j * 64; }
; #pragma unroll
;         for (int i = 0; i < 2; ++i) { const int id = tid + i * NT; rk[i] = *(const u32x4*)(it.kn + (size_t)(rowb + (id >> 4)) * it.ldk + (id & 15) * 8);
;             rv[i] = *(const u32x4*)(it.vt + (size_t)(id >> 3) * KEYS + vcol + (id & 7) * 8); }
;         if (DQ == 192) rr = *(const u32x4*)(it.kr + (size_t)(rowb + (tid >> 3)) * UC + (tid & 7) * 8);
;     };
.Lfast_1352:
	s_ashr_i32 s7, s6, 31
	s_lshl_b64 s[6:7], s[6:7], 1
	s_lshl_b32 s98, s13, 11
	s_mov_b32 s99, 0
	s_mul_i32 s100, s13, 0x1a00
	s_mov_b32 s101, 0
	v_lshl_add_u64 v[148:149], v[198:199], 0, s[100:101]
	v_lshl_add_u64 v[152:153], v[170:171], 0, s[6:7]
	v_lshl_add_u64 v[156:157], v[196:197], 0, s[98:99]
	v_lshl_add_u64 v[160:161], v[168:169], 0, s[6:7]
	v_lshl_add_u64 v[164:165], v[194:195], 0, s[98:99]
	global_load_dwordx4 v[148:151], v[148:149], off
	s_nop 0
	global_load_dwordx4 v[152:155], v[152:153], off
	s_nop 0
	global_load_dwordx4 v[156:159], v[156:157], off
	s_nop 0
	global_load_dwordx4 v[160:163], v[160:161], off
	s_nop 0
	global_load_dwordx4 v[164:167], v[164:165], off
	s_waitcnt lgkmcnt(0)
	s_barrier

; template <int DQ>
; DI void attn_item(const Frame& F, const AttnItem& it, const LAS float* rpb_lds) {
;     ...
;     auto gload = [&](int ti) {
;         int rowb, vcol;
;         if (ti < it.ntl) { const int kt = it.t0 + ti; rowb = it.lat_row0 + kt * 64; vcol = kt * 64; } else { const int j = ti - it.ntl; rowb = it.ctx_row0 + j * 64; vcol = SEQ + j * 64; }
; #pragma unroll
;         for (int i = 0; i < 2; ++i) { const int id = tid + i * NT; rk[i] = *(const u32x4*)(it.kn + (size_t)(rowb + (id >> 4)) * it.ldk + (id & 15) * 8);
;             rv[i] = *(const u32x4*)(it.vt + (size_t)(id >> 3) * KEYS + vcol + (id & 7) * 8); }
;         if (DQ == 192) rr = *(const u32x4*)(it.kr + (size_t)(rowb + (tid >> 3)) * UC + (tid & 7) * 8);
;     };
.Lfast_1360:
	s_ashr_i32 s13, s12, 31
	s_lshl_b64 s[12:13], s[12:13], 1
	s_lshl_b32 s98, s21, 11
	s_mov_b32 s99, 0
	s_mul_i32 s100, s21, 0x1a00
	s_mov_b32 s101, 0
	v_lshl_add_u64 v[148:149], v[198:199], 0, s[100:101]
	v_lshl_add_u64 v[152:153], v[170:171], 0, s[12:13]
	v_lshl_add_u64 v[156:157], v[196:197], 0, s[98:99]
	v_lshl_add_u64 v[160:161], v[168:169], 0, s[12:13]
	v_lshl_add_u64 v[164:165], v[194:195], 0, s[98:99]
	global_load_dwordx4 v[148:151], v[148:149], off
	s_nop 0
	global_load_dwordx4 v[152:155], v[152:153], off
	s_nop 0
	global_load_dwordx4 v[156:159], v[156:157], off
	s_nop 0
	global_load_dwordx4 v[160:163], v[160:161], off
	s_nop 0
	global_load_dwordx4 v[164:167], v[164:165], off
	s_waitcnt lgkmcnt(0)
	s_barrier
